# adds NSA half-tile stagger (waves 4-7 take the per-tile barrier after QK) on top of batched epilogue/merge loads
# speedup vs baseline: 1.0041x; 1.0041x over previous
; #define LAS __attribute__((address_space(3)))
; __global__ void __launch_bounds__(NWAVES * 64, 2) fwd(Args a) {
;     extern __shared__ __attribute__((aligned(16))) unsigned char lds_raw[];
;     LAS unsigned char* lds = (LAS unsigned char*)lds_raw;
;     const int tid = threadIdx.x, lane = tid & 63, wave = __builtin_amdgcn_readfirstlane(tid >> 6);
;     const int G = gridDim.x; const int bx = blockIdx.x; const int vcu = (G % 8 == 0) ? (bx % 8) * (G / 8) + bx / 8 : bx;
;     const int gw = vcu * NWAVES + wave, NGW = G * NWAVES;
;     unsigned char* ws = a.ws;
;     unsigned* ctl = (unsigned*)(ws + WS_CTL);
;     volatile LAS unsigned* MISC = (volatile LAS unsigned*)(lds + MISC_OFF);
;     for (int u = tid; u < (LDS_BYTES - RING_BYTES) / 4; u += NWAVES * 64) ((LAS unsigned*)(lds + RING_BYTES))[u] = 0u;
;     __syncthreads();
;     const int lo = a.ph_lo & 255, hi = a.ph_hi, qsel = a.ph_lo >> 8;
;     const bool use_bar = (hi - lo) > 1;
;     XcdBarrier bar; bar.bar = ctl + CW_BAR; bar.x = 0; bar.st = nullptr;
;     if (use_bar) bar = xcd_barrier_post(ctl + CW_BAR, MISC + 8);
_Z3fwd4Args:
	s_load_dwordx2 s[94:95], s[0:1], 0xf0
	s_load_dwordx4 s[4:7], s[0:1], 0xe0
	s_mov_b32 s74, s2
	v_readfirstlane_b32 s2, v0
	s_waitcnt lgkmcnt(0)
	v_writelane_b32 v253, s4, 0
	s_nop 1
	v_writelane_b32 v253, s5, 1
	v_writelane_b32 v253, s6, 2
	v_writelane_b32 v253, s7, 3
	s_load_dword s73, s[0:1], 0x100
	s_load_dwordx8 s[4:11], s[0:1], 0xc0
	s_waitcnt lgkmcnt(0)
	v_writelane_b32 v253, s4, 4
	s_nop 1
	v_writelane_b32 v253, s5, 5
	v_writelane_b32 v253, s6, 6
	v_writelane_b32 v253, s7, 7
	v_writelane_b32 v253, s8, 8
	v_writelane_b32 v253, s9, 9
	v_writelane_b32 v253, s10, 10
	v_writelane_b32 v253, s11, 11
	s_add_u32 s6, s0, 0x100
	v_writelane_b32 v253, s2, 12
	s_addc_u32 s7, s1, 0
	s_lshr_b32 s98, s2, 8
	s_mov_b32 s99, 0
	s_and_b32 s2, s73, 7
	s_cmp_lg_u32 s2, 0
	s_mov_b32 s10, s74
	s_cbranch_scc1 .LBB0_2
	s_ashr_i32 s3, s74, 31
	s_lshr_b32 s3, s3, 29
	s_add_i32 s3, s74, s3
	s_and_b32 s4, s3, -8
	s_ashr_i32 s2, s73, 3
	s_sub_i32 s4, s74, s4
	s_mul_i32 s2, s2, s4
	s_ashr_i32 s3, s3, 3
	s_add_i32 s10, s2, s3

; #define VM_WAIT() asm volatile("s_waitcnt vmcnt(0)" ::: "memory")
; DI void nsa_unit(const Args& a, LAS unsigned char* lds, int b, int g, int jb) {
;     ...
;             if (issued) asm volatile("s_waitcnt vmcnt(4)" ::: "memory"); else VM_WAIT();
;             __syncthreads();
;             scur = scur == 5 ? 0 : scur + 1;
;         }
.LBB0_1991:
	s_add_i32 s0, s19, 1
	s_cmp_lg_u32 s19, 5
	s_cselect_b32 s19, s0, 0
	s_or_b32 s0, s14, s97
	s_cmp_eq_u32 s99, 0
	s_cbranch_scc0 .Lnsa_nobar
	s_waitcnt vmcnt(0) lgkmcnt(0)
	s_barrier
.Lnsa_nobar:
	s_mov_b32 s99, 0
	s_cmp_lg_u32 s0, 0
	s_cbranch_scc0 .LBB0_2077

; #define LAS __attribute__((address_space(3)))
; #define MFMA32(a, b, c) __builtin_amdgcn_mfma_f32_32x32x16_bf16((a), (b), (c), 0, 0, 0)
; template <bool NEAR, int MASK>
; DI void nsa_tile2(f32x16 (&O)[2], float& l, float& inited, f32x16& negm, const LAS unsigned char* Kb, const LAS unsigned char* Vb, const int (&ka)[4], const int (&va)[4], const bf16x8 (&qf)[4],
;                   const LAS float* lutp, float c31, int dlim, bool tok) {
;     f32x16 S[2];
; #pragma unroll
;     for (int rb = 0; rb < 2; ++rb) { const bf16x8 kf0 = *(const LAS bf16x8*)(Kb + ka[0] + rb * 4096); S[rb] = MFMA32(kf0, qf[0], negm);
; #pragma unroll
;         for (int ks = 1; ks < 4; ++ks) { const bf16x8 kf = *(const LAS bf16x8*)(Kb + ka[ks] + rb * 4096); S[rb] = MFMA32(kf, qf[ks], S[rb]); } }
;     float mx = -INFINITY;
; #pragma unroll
;     for (int rb = 0; rb < 2; ++rb)
; #pragma unroll
;         for (int reg = 0; reg < 16; ++reg) { const int c = 32 * rb + (reg & 3) + 8 * (reg >> 2); float sv = S[rb][reg];
;             if (NEAR) sv += lutp[c]; else sv += c31;
;             if (MASK == 1) sv = c <= dlim ? sv : -INFINITY;
;             if (MASK == 2) sv = c > dlim - 512 ? sv : -INFINITY;
;             S[rb][reg] = sv; mx = fmaxf(mx, sv); }
; DI void nsa_unit(const Args& a, LAS unsigned char* lds, int b, int g, int jb) {
;     ...
;             int boff = NSA_SLOT(scur);
;             asm volatile("" : "+s"(boff));
;             const LAS unsigned char* Kb = lds + boff; const LAS unsigned char* Vb = Kb + 8192;
;             const int key0 = 64 * kt, dlim = t - key0 - 4 * h2;
;             const LAS float* lutp = lut + (LOFF - dlim);
;             const bool tok = isw ? true : ((tmask >> kt) & 1u) != 0u;
;             if (__ballot(tok) != 0ull) {
;                 if (kt == jb) nsa_tile2<true, 1>(O, l, inited, negm, Kb, Vb, ka, va, qf, lutp, c31, dlim, tok);
;                 else if (isw && kt == jb - 8) nsa_tile2<true, 2>(O, l, inited, negm, Kb, Vb, ka, va, qf, lutp, c31, dlim, tok);
.LBB0_2040:
	v_lshrrev_b32_e32 v3, s12, v142
	v_and_b32_e32 v3, 1, v3
	v_cmp_eq_u32_e64 s[4:5], 1, v3
	s_xor_b64 s[2:3], s[0:1], -1
	s_or_b64 s[2:3], s[2:3], s[4:5]
	v_cndmask_b32_e64 v3, 0, 1, s[2:3]
	v_cmp_ne_u32_e32 vcc, 0, v3
	s_cbranch_vccz .LBB0_2070
	s_lshl_b32 s21, s12, 6
	v_or_b32_e32 v3, s21, v222
	v_sub_u32_e32 v3, v150, v3
	s_add_i32 s20, s6, 0
	v_lshlrev_b32_e32 v4, 2, v3
	v_sub_u32_e32 v233, s86, v4
	s_mov_b64 s[6:7], -1
	s_cmp_lg_u32 s12, s73
	v_add_u32_e32 v234, s20, v225
	s_cbranch_scc0 .LBB0_2063
	ds_read_b128 v[4:7], v234
	s_cmp_lg_u32 s12, s17
	s_cselect_b64 s[6:7], -1, 0
	s_or_b64 s[12:13], s[0:1], s[6:7]
	s_mov_b64 s[6:7], -1
	s_and_b64 vcc, exec, s[12:13]
	s_cbranch_vccnz .LBB0_2049
	v_add_u32_e32 v12, s20, v223
	ds_read_b128 v[8:11], v12
	v_add_u32_e32 v13, s20, v224
	v_add_u32_e32 v14, s20, v226
	s_movk_i32 s6, 0x200
	v_cmp_gt_i32_e32 vcc, s6, v3
	s_movk_i32 s6, 0x201
	v_cmp_gt_i32_e64 s[6:7], s6, v3
	s_waitcnt lgkmcnt(0)
	v_mfma_f32_32x32x16_bf16 v[66:81], v[8:11], v[114:117], v[82:97]
	ds_read_b128 v[8:11], v13
	s_waitcnt lgkmcnt(0)
	v_mfma_f32_32x32x16_bf16 v[66:81], v[8:11], v[118:121], v[66:81]
	ds_read_b128 v[8:11], v14
	v_mfma_f32_32x32x16_bf16 v[66:81], v[4:7], v[122:125], v[66:81]
	s_waitcnt lgkmcnt(0)
	v_mfma_f32_32x32x16_bf16 v[66:81], v[8:11], v[126:129], v[66:81]
	ds_read_b128 v[8:11], v12 offset:4096
	s_waitcnt lgkmcnt(0)
	v_mfma_f32_32x32x16_bf16 v[50:65], v[8:11], v[114:117], v[82:97]
	ds_read_b128 v[8:11], v13 offset:4096
	s_waitcnt lgkmcnt(0)
	v_mfma_f32_32x32x16_bf16 v[50:65], v[8:11], v[118:121], v[50:65]
	ds_read_b128 v[8:11], v234 offset:4096
	s_waitcnt lgkmcnt(0)
	v_mfma_f32_32x32x16_bf16 v[50:65], v[8:11], v[122:125], v[50:65]
	ds_read_b128 v[8:11], v14 offset:4096
	s_waitcnt lgkmcnt(0)
	v_mfma_f32_32x32x16_bf16 v[50:65], v[8:11], v[126:129], v[50:65]
	s_cmp_eq_u32 s98, 0
	s_cbranch_scc1 .Lnsa_nomid_a
	s_waitcnt vmcnt(0) lgkmcnt(0)
	s_barrier
	s_mov_b32 s99, 1
.Lnsa_nomid_a:
	v_add_u32_e32 v8, 0x8e4c, v233
	ds_read2_b32 v[8:9], v8 offset1:1
	s_waitcnt lgkmcnt(0)
	v_add_f32_e64 v10, v66, v8
	v_add_f32_e64 v11, v67, v9
	v_cndmask_b32_e32 v9, v221, v10, vcc
	v_add_u32_e32 v10, 0x8e54, v233
	v_cndmask_b32_e64 v8, v221, v11, s[6:7]
	ds_read2_b32 v[10:11], v10 offset1:1
	s_mov_b32 s6, 0xff800000
	v_max3_f32 v14, v9, s6, v8
	s_movk_i32 s6, 0x202
	v_cmp_gt_i32_e32 vcc, s6, v3
	s_movk_i32 s6, 0x203
	s_waitcnt lgkmcnt(0)
	v_pk_add_f32 v[12:13], v[68:69], v[10:11]
	v_cmp_gt_i32_e64 s[6:7], s6, v3
	v_cndmask_b32_e32 v11, v221, v12, vcc
	v_add_u32_e32 v12, 0x8e6c, v233
	v_cndmask_b32_e64 v10, v221, v13, s[6:7]
	ds_read2_b32 v[12:13], v12 offset1:1
	s_movk_i32 s6, 0x208
	v_cmp_gt_i32_e32 vcc, s6, v3
	s_movk_i32 s6, 0x209
	v_cmp_gt_i32_e64 s[6:7], s6, v3
	s_waitcnt lgkmcnt(0)
	v_pk_add_f32 v[12:13], v[70:71], v[12:13]
	v_max3_f32 v14, v14, v11, v10
	v_cndmask_b32_e32 v130, v221, v12, vcc
	v_add_u32_e32 v12, 0x8e74, v233
	v_cndmask_b32_e64 v17, v221, v13, s[6:7]
	ds_read2_b32 v[12:13], v12 offset1:1
	s_movk_i32 s6, 0x20a
	v_cmp_gt_i32_e32 vcc, s6, v3
	s_movk_i32 s6, 0x20b
	v_cmp_gt_i32_e64 s[6:7], s6, v3
	s_waitcnt lgkmcnt(0)
	v_pk_add_f32 v[12:13], v[72:73], v[12:13]
	v_max3_f32 v14, v14, v130, v17
	v_cndmask_b32_e32 v132, v221, v12, vcc
	v_add_u32_e32 v12, 0x8e8c, v233
	v_cndmask_b32_e64 v131, v221, v13, s[6:7]
	ds_read2_b32 v[12:13], v12 offset1:1
	s_movk_i32 s6, 0x210
	v_cmp_gt_i32_e32 vcc, s6, v3
	s_movk_i32 s6, 0x211
	v_cmp_gt_i32_e64 s[6:7], s6, v3
	s_waitcnt lgkmcnt(0)
	v_pk_add_f32 v[12:13], v[74:75], v[12:13]
	v_max3_f32 v14, v14, v132, v131
	v_cndmask_b32_e32 v140, v221, v12, vcc
	v_add_u32_e32 v12, 0x8e94, v233
	v_cndmask_b32_e64 v137, v221, v13, s[6:7]
	ds_read2_b32 v[12:13], v12 offset1:1
	s_movk_i32 s6, 0x212
	v_cmp_gt_i32_e32 vcc, s6, v3
	s_movk_i32 s6, 0x213
	v_cmp_gt_i32_e64 s[6:7], s6, v3
	s_waitcnt lgkmcnt(0)
	v_pk_add_f32 v[12:13], v[76:77], v[12:13]
	v_max3_f32 v14, v14, v140, v137
	v_cndmask_b32_e32 v192, v221, v12, vcc
	v_add_u32_e32 v12, 0x8eac, v233
	v_cndmask_b32_e64 v141, v221, v13, s[6:7]
	ds_read2_b32 v[12:13], v12 offset1:1
	s_movk_i32 s6, 0x218
	v_cmp_gt_i32_e32 vcc, s6, v3
	s_movk_i32 s6, 0x219
	v_cmp_gt_i32_e64 s[6:7], s6, v3
	s_waitcnt lgkmcnt(0)
	v_pk_add_f32 v[12:13], v[78:79], v[12:13]
	v_max3_f32 v14, v14, v192, v141
	v_cndmask_b32_e32 v196, v221, v12, vcc
	v_add_u32_e32 v12, 0x8eb4, v233
	v_cndmask_b32_e64 v193, v221, v13, s[6:7]
	ds_read2_b32 v[12:13], v12 offset1:1
	s_movk_i32 s6, 0x21a
	v_cmp_gt_i32_e32 vcc, s6, v3
	s_movk_i32 s6, 0x21b
	v_cmp_gt_i32_e64 s[6:7], s6, v3
	s_waitcnt lgkmcnt(0)
	v_pk_add_f32 v[12:13], v[80:81], v[12:13]
	v_max3_f32 v14, v14, v196, v193
	v_cndmask_b32_e32 v199, v221, v12, vcc
	v_add_u32_e32 v12, 0x8ecc, v233
	v_cndmask_b32_e64 v197, v221, v13, s[6:7]
	ds_read2_b32 v[12:13], v12 offset1:1
	s_movk_i32 s6, 0x220
	v_cmp_gt_i32_e32 vcc, s6, v3
	s_movk_i32 s6, 0x221
	v_cmp_gt_i32_e64 s[6:7], s6, v3
	s_waitcnt lgkmcnt(0)
	v_pk_add_f32 v[12:13], v[50:51], v[12:13]
	v_max3_f32 v15, v14, v199, v197
	v_cndmask_b32_e32 v201, v221, v12, vcc
	v_add_u32_e32 v12, 0x8ed4, v233
	v_cndmask_b32_e64 v14, v221, v13, s[6:7]
	ds_read2_b32 v[12:13], v12 offset1:1
	s_movk_i32 s6, 0x222
	v_cmp_gt_i32_e32 vcc, s6, v3
	s_movk_i32 s6, 0x223
	v_cmp_gt_i32_e64 s[6:7], s6, v3
	s_waitcnt lgkmcnt(0)
; DI float ex2(float x) { return __builtin_amdgcn_exp2f(x); }
; template <bool NEAR, int MASK>
; DI void nsa_tile2(f32x16 (&O)[2], float& l, float& inited, f32x16& negm, const LAS unsigned char* Kb, const LAS unsigned char* Vb, const int (&ka)[4], const int (&va)[4], const bf16x8 (&qf)[4],
;                   const LAS float* lutp, float c31, int dlim, bool tok) {
;     ...
;         for (int reg = 0; reg < 16; ++reg) { const int c = 32 * rb + (reg & 3) + 8 * (reg >> 2); float sv = S[rb][reg];
;             if (NEAR) sv += lutp[c]; else sv += c31;
;             if (MASK == 1) sv = c <= dlim ? sv : -INFINITY;
;             if (MASK == 2) sv = c > dlim - 512 ? sv : -INFINITY;
;             S[rb][reg] = sv; mx = fmaxf(mx, sv); }
;     mx = tok ? mx : -INFINITY;
;     mx = pairmax32(mx);
;     const bool need = mx > RESC_THR || (inited == 0.f && mx > -INFINITY);
;     if (__builtin_amdgcn_ballot_w64(need) != 0ull) {
;         float delta = 0.f;
;         if (mx > -INFINITY) { delta = inited == 0.f ? mx : fmaxf(mx, 0.f); inited = 1.f; }
;         const float alpha = ex2(-delta);
;         l *= alpha;
; #pragma unroll
;         for (int reg = 0; reg < 16; ++reg) { O[0][reg] *= alpha; O[1][reg] *= alpha; negm[reg] -= delta; S[0][reg] -= delta; S[1][reg] -= delta; }
;     }
	v_pk_add_f32 v[50:51], v[52:53], v[12:13]
	v_max3_f32 v15, v15, v201, v14
	v_cndmask_b32_e64 v12, v221, v51, s[6:7]
	v_cndmask_b32_e32 v13, v221, v50, vcc
	v_max3_f32 v52, v15, v13, v12
	v_add_u32_e32 v15, 0x8eec, v233
	ds_read2_b32 v[50:51], v15 offset1:1
	s_movk_i32 s6, 0x228
	v_cmp_gt_i32_e32 vcc, s6, v3
	s_movk_i32 s6, 0x229
	v_cmp_gt_i32_e64 s[6:7], s6, v3
	s_waitcnt lgkmcnt(0)
	v_pk_add_f32 v[50:51], v[54:55], v[50:51]
	s_nop 0
	v_cndmask_b32_e32 v16, v221, v50, vcc
	v_add_u32_e32 v50, 0x8ef4, v233
	v_cndmask_b32_e64 v15, v221, v51, s[6:7]
	ds_read2_b32 v[50:51], v50 offset1:1
	s_movk_i32 s6, 0x22a
	v_cmp_gt_i32_e32 vcc, s6, v3
	s_movk_i32 s6, 0x22b
	v_cmp_gt_i32_e64 s[6:7], s6, v3
	s_waitcnt lgkmcnt(0)
	v_pk_add_f32 v[50:51], v[56:57], v[50:51]
	v_max3_f32 v52, v52, v16, v15
	v_cndmask_b32_e32 v134, v221, v50, vcc
	v_add_u32_e32 v50, 0x8f0c, v233
	v_cndmask_b32_e64 v133, v221, v51, s[6:7]
	ds_read2_b32 v[50:51], v50 offset1:1
	s_movk_i32 s6, 0x230
	v_cmp_gt_i32_e32 vcc, s6, v3
	s_movk_i32 s6, 0x231
	v_cmp_gt_i32_e64 s[6:7], s6, v3
	s_waitcnt lgkmcnt(0)
	v_pk_add_f32 v[50:51], v[58:59], v[50:51]
	v_max3_f32 v52, v52, v134, v133
	v_cndmask_b32_e32 v136, v221, v50, vcc
	v_add_u32_e32 v50, 0x8f14, v233
	v_cndmask_b32_e64 v135, v221, v51, s[6:7]
	ds_read2_b32 v[50:51], v50 offset1:1
	s_movk_i32 s6, 0x232
	v_cmp_gt_i32_e32 vcc, s6, v3
	s_movk_i32 s6, 0x233
	v_cmp_gt_i32_e64 s[6:7], s6, v3
	s_waitcnt lgkmcnt(0)
	v_pk_add_f32 v[50:51], v[60:61], v[50:51]
	v_max3_f32 v52, v52, v136, v135
	v_cndmask_b32_e32 v139, v221, v50, vcc
	v_add_u32_e32 v50, 0x8f2c, v233
	v_cndmask_b32_e64 v138, v221, v51, s[6:7]
	ds_read2_b32 v[50:51], v50 offset1:1
	s_movk_i32 s6, 0x238
	v_cmp_gt_i32_e32 vcc, s6, v3
	s_movk_i32 s6, 0x239
	v_cmp_gt_i32_e64 s[6:7], s6, v3
	s_waitcnt lgkmcnt(0)
	v_pk_add_f32 v[50:51], v[62:63], v[50:51]
	v_max3_f32 v52, v52, v139, v138
	v_cndmask_b32_e32 v195, v221, v50, vcc
	v_add_u32_e32 v50, 0x8f34, v233
	v_cndmask_b32_e64 v194, v221, v51, s[6:7]
	ds_read2_b32 v[50:51], v50 offset1:1
	s_movk_i32 s6, 0x23a
	v_cmp_gt_i32_e32 vcc, s6, v3
	s_movk_i32 s6, 0x23b
	v_cmp_gt_i32_e64 s[6:7], s6, v3
	s_waitcnt lgkmcnt(0)
	v_pk_add_f32 v[50:51], v[64:65], v[50:51]
	v_max3_f32 v52, v52, v195, v194
	v_cndmask_b32_e64 v198, v221, v51, s[6:7]
	v_cndmask_b32_e32 v200, v221, v50, vcc
	v_max3_f32 v50, v52, v200, v198
	v_mov_b32_e32 v51, v50
	s_nop 1
	v_permlane32_swap_b32_e32 v50, v51
	v_cmp_nlt_f32_e32 vcc, s67, v50
	s_mov_b64 s[6:7], -1
	s_and_saveexec_b64 s[12:13], vcc
	s_mov_b32 s6, 0xff800000
	v_cmp_eq_f32_e32 vcc, 0, v232
	v_cmp_lg_f32_e64 s[6:7], s6, v50
	s_and_b64 s[6:7], vcc, s[6:7]
	s_orn2_b64 s[6:7], s[6:7], exec
	s_or_b64 exec, exec, s[12:13]
	v_cndmask_b32_e64 v51, 0, 1, s[6:7]
	v_cmp_ne_u32_e32 vcc, 0, v51
	s_cbranch_vccz .LBB0_2047
	v_max_f32_e32 v51, v50, v50
	v_max_f32_e32 v51, 0, v51
	v_cmp_eq_f32_e32 vcc, 0, v232
	s_mov_b32 s6, 0xff800000
	s_nop 0
	v_cndmask_b32_e32 v51, v51, v50, vcc
	v_cmp_nlg_f32_e32 vcc, s6, v50
	s_nop 1
	v_cndmask_b32_e64 v203, v51, 0, vcc
	v_exp_f32_e64 v50, -v203
	v_cndmask_b32_e32 v235, 1.0, v232, vcc
	v_sub_f32_e32 v113, v97, v203
	v_sub_f32_e32 v112, v96, v203
	v_mul_f32_e32 v202, v231, v50
	v_pk_mul_f32 v[80:81], v[48:49], v[50:51] op_sel_hi:[1,0]
	v_pk_mul_f32 v[78:79], v[46:47], v[50:51] op_sel_hi:[1,0]
	v_pk_mul_f32 v[76:77], v[44:45], v[50:51] op_sel_hi:[1,0]
	v_pk_mul_f32 v[74:75], v[42:43], v[50:51] op_sel_hi:[1,0]
	v_pk_mul_f32 v[72:73], v[40:41], v[50:51] op_sel_hi:[1,0]
	v_pk_mul_f32 v[70:71], v[38:39], v[50:51] op_sel_hi:[1,0]
	v_pk_mul_f32 v[68:69], v[36:37], v[50:51] op_sel_hi:[1,0]
	v_pk_mul_f32 v[66:67], v[34:35], v[50:51] op_sel_hi:[1,0]
	v_pk_mul_f32 v[64:65], v[32:33], v[50:51] op_sel_hi:[1,0]
	v_pk_mul_f32 v[62:63], v[30:31], v[50:51] op_sel_hi:[1,0]
	v_pk_mul_f32 v[60:61], v[28:29], v[50:51] op_sel_hi:[1,0]
	v_pk_mul_f32 v[58:59], v[26:27], v[50:51] op_sel_hi:[1,0]
	v_pk_mul_f32 v[56:57], v[24:25], v[50:51] op_sel_hi:[1,0]
	v_pk_mul_f32 v[54:55], v[22:23], v[50:51] op_sel_hi:[1,0]
	v_pk_mul_f32 v[52:53], v[20:21], v[50:51] op_sel_hi:[1,0]
	v_pk_mul_f32 v[50:51], v[18:19], v[50:51] op_sel_hi:[1,0]
	v_sub_f32_e32 v111, v95, v203
	v_sub_f32_e32 v110, v94, v203
	v_sub_f32_e32 v109, v93, v203
	v_sub_f32_e32 v108, v92, v203
	v_sub_f32_e32 v107, v91, v203
	v_sub_f32_e32 v106, v90, v203
	v_sub_f32_e32 v105, v89, v203
	v_sub_f32_e32 v104, v88, v203
	v_sub_f32_e32 v103, v87, v203
	v_sub_f32_e32 v102, v86, v203
	v_sub_f32_e32 v101, v85, v203
	v_sub_f32_e32 v100, v84, v203
	v_sub_f32_e32 v99, v83, v203
	v_sub_f32_e32 v98, v82, v203
	v_sub_f32_e32 v9, v9, v203
	v_sub_f32_e32 v8, v8, v203
	v_sub_f32_e32 v11, v11, v203
	v_sub_f32_e32 v10, v10, v203
	v_sub_f32_e32 v130, v130, v203
	v_sub_f32_e32 v17, v17, v203
	v_sub_f32_e32 v132, v132, v203
	v_sub_f32_e32 v131, v131, v203
	v_sub_f32_e32 v140, v140, v203
	v_sub_f32_e32 v137, v137, v203
	v_sub_f32_e32 v192, v192, v203
	v_sub_f32_e32 v141, v141, v203
	v_sub_f32_e32 v196, v196, v203
	v_sub_f32_e32 v193, v193, v203
	v_sub_f32_e32 v199, v199, v203
	v_sub_f32_e32 v197, v197, v203
	v_sub_f32_e32 v201, v201, v203
	v_sub_f32_e32 v14, v14, v203
	v_sub_f32_e32 v13, v13, v203
	v_sub_f32_e32 v12, v12, v203
	v_sub_f32_e32 v16, v16, v203
	v_sub_f32_e32 v15, v15, v203
	v_sub_f32_e32 v134, v134, v203
	v_sub_f32_e32 v133, v133, v203
	v_sub_f32_e32 v136, v136, v203
	v_sub_f32_e32 v135, v135, v203
	v_sub_f32_e32 v139, v139, v203
	v_sub_f32_e32 v138, v138, v203
	v_sub_f32_e32 v195, v195, v203
	v_sub_f32_e32 v194, v194, v203
	v_sub_f32_e32 v200, v200, v203
	v_sub_f32_e32 v198, v198, v203
	s_branch .LBB0_2048

; #define LAS __attribute__((address_space(3)))
; #define MFMA32(a, b, c) __builtin_amdgcn_mfma_f32_32x32x16_bf16((a), (b), (c), 0, 0, 0)
; template <bool NEAR, int MASK>
; DI void nsa_tile2(f32x16 (&O)[2], float& l, float& inited, f32x16& negm, const LAS unsigned char* Kb, const LAS unsigned char* Vb, const int (&ka)[4], const int (&va)[4], const bf16x8 (&qf)[4],
;                   const LAS float* lutp, float c31, int dlim, bool tok) {
;     f32x16 S[2];
; #pragma unroll
;     for (int rb = 0; rb < 2; ++rb) { const bf16x8 kf0 = *(const LAS bf16x8*)(Kb + ka[0] + rb * 4096); S[rb] = MFMA32(kf0, qf[0], negm);
; #pragma unroll
;         for (int ks = 1; ks < 4; ++ks) { const bf16x8 kf = *(const LAS bf16x8*)(Kb + ka[ks] + rb * 4096); S[rb] = MFMA32(kf, qf[ks], S[rb]); } }
;     float mx = -INFINITY;
; #pragma unroll
;     for (int rb = 0; rb < 2; ++rb)
; #pragma unroll
;         for (int reg = 0; reg < 16; ++reg) { const int c = 32 * rb + (reg & 3) + 8 * (reg >> 2); float sv = S[rb][reg];
;             if (NEAR) sv += lutp[c]; else sv += c31;
;             if (MASK == 1) sv = c <= dlim ? sv : -INFINITY;
;             if (MASK == 2) sv = c > dlim - 512 ? sv : -INFINITY;
;             S[rb][reg] = sv; mx = fmaxf(mx, sv); }
; DI void nsa_unit(const Args& a, LAS unsigned char* lds, int b, int g, int jb) {
;     ...
;                 else if (!isw && key0 + 63 + 790 <= q0 + 32 * th) nsa_tile2<false, 0>(O, l, inited, negm, Kb, Vb, ka, va, qf, lutp, c31, dlim, tok);
;                 else nsa_tile2<true, 0>(O, l, inited, negm, Kb, Vb, ka, va, qf, lutp, c31, dlim, tok);
.LBB0_2049:
	s_and_b64 vcc, exec, s[6:7]
	s_cbranch_vccz .LBB0_2062
	v_add_u32_e32 v12, s20, v223
	v_add_u32_e32 v237, s20, v224
	v_add_u32_e32 v236, s20, v226
	ds_read_b128 v[130:133], v237
	ds_read_b128 v[8:11], v236
	ds_read_b128 v[134:137], v12
	ds_read_b128 v[12:15], v12 offset:4096
	s_cmp_le_i32 s21, s18
	s_cselect_b64 s[6:7], -1, 0
	s_and_b64 s[0:1], s[0:1], s[6:7]
	s_andn2_b64 vcc, exec, s[0:1]
	s_mov_b64 s[0:1], -1
	s_cbranch_vccz .LBB0_2057
	s_waitcnt lgkmcnt(0)
	v_mfma_f32_32x32x16_bf16 v[58:73], v[134:137], v[114:117], v[82:97]
	v_add_u32_e32 v16, 0x8e4c, v233
	v_add_u32_e32 v50, 0x8e54, v233
	v_add_u32_e32 v52, 0x8e6c, v233
	v_add_u32_e32 v54, 0x8e74, v233
	ds_read_b128 v[78:81], v234 offset:4096
	ds_read_b128 v[98:101], v237 offset:4096
	ds_read_b128 v[74:77], v236 offset:4096
	ds_read2_b32 v[16:17], v16 offset1:1
	ds_read2_b32 v[50:51], v50 offset1:1
	ds_read2_b32 v[52:53], v52 offset1:1
	ds_read2_b32 v[54:55], v54 offset1:1
	s_mov_b32 s0, 0xff800000
	v_mfma_f32_32x32x16_bf16 v[58:73], v[130:133], v[118:121], v[58:73]
	v_add_u32_e32 v56, 0x8e8c, v233
	ds_read2_b32 v[102:103], v56 offset1:1
	v_add_u32_e32 v104, 0x8e94, v233
	v_add_u32_e32 v106, 0x8eac, v233
	v_add_u32_e32 v108, 0x8eb4, v233
	ds_read2_b32 v[104:105], v104 offset1:1
	ds_read2_b32 v[106:107], v106 offset1:1
	ds_read2_b32 v[108:109], v108 offset1:1
	s_mov_b64 s[6:7], -1
	v_mfma_f32_32x32x16_bf16 v[58:73], v[4:7], v[122:125], v[58:73]
	v_mfma_f32_32x32x16_bf16 v[58:73], v[8:11], v[126:129], v[58:73]
	s_waitcnt lgkmcnt(0)
	s_nop 10
	v_pk_add_f32 v[202:203], v[58:59], v[16:17]
	v_pk_add_f32 v[198:199], v[60:61], v[50:51]
	v_max3_f32 v50, v202, s0, v203
	v_pk_add_f32 v[138:139], v[62:63], v[52:53]
	v_max3_f32 v50, v50, v198, v199
	v_pk_add_f32 v[16:17], v[64:65], v[54:55]
	v_max3_f32 v50, v50, v138, v139
	v_max3_f32 v110, v50, v16, v17
	v_mfma_f32_32x32x16_bf16 v[50:65], v[12:15], v[114:117], v[82:97]
	v_add_f32_e64 v204, v66, v102
	v_add_f32_e64 v205, v67, v103
	v_add_f32_e64 v196, v68, v104
	v_add_f32_e64 v197, v69, v105
	v_max3_f32 v66, v110, v204, v205
	v_max3_f32 v66, v66, v196, v197
	v_pk_add_f32 v[140:141], v[70:71], v[106:107]
	v_pk_add_f32 v[192:193], v[72:73], v[108:109]
	v_max3_f32 v66, v66, v140, v141
	v_mfma_f32_32x32x16_bf16 v[50:65], v[98:101], v[118:121], v[50:65]
	v_max3_f32 v98, v66, v192, v193
	v_add_u32_e32 v66, 0x8ecc, v233
	v_add_u32_e32 v68, 0x8ed4, v233
	v_add_u32_e32 v70, 0x8eec, v233
	v_add_u32_e32 v72, 0x8ef4, v233
	ds_read2_b32 v[66:67], v66 offset1:1
	ds_read2_b32 v[68:69], v68 offset1:1
	ds_read2_b32 v[70:71], v70 offset1:1
	ds_read2_b32 v[72:73], v72 offset1:1
	v_mfma_f32_32x32x16_bf16 v[50:65], v[78:81], v[122:125], v[50:65]
	v_mfma_f32_32x32x16_bf16 v[50:65], v[74:77], v[126:129], v[50:65]
	s_cmp_eq_u32 s98, 0
	s_cbranch_scc1 .Lnsa_nomid_b
	s_waitcnt vmcnt(0) lgkmcnt(0)
	s_barrier
	s_mov_b32 s99, 1
; DI float ex2(float x) { return __builtin_amdgcn_exp2f(x); }
; template <bool NEAR, int MASK>
; DI void nsa_tile2(f32x16 (&O)[2], float& l, float& inited, f32x16& negm, const LAS unsigned char* Kb, const LAS unsigned char* Vb, const int (&ka)[4], const int (&va)[4], const bf16x8 (&qf)[4],
;                   const LAS float* lutp, float c31, int dlim, bool tok) {
;     ...
;     float mx = -INFINITY;
; #pragma unroll
;     for (int rb = 0; rb < 2; ++rb)
; #pragma unroll
;         for (int reg = 0; reg < 16; ++reg) { const int c = 32 * rb + (reg & 3) + 8 * (reg >> 2); float sv = S[rb][reg];
;             if (NEAR) sv += lutp[c]; else sv += c31;
;             if (MASK == 1) sv = c <= dlim ? sv : -INFINITY;
;             if (MASK == 2) sv = c > dlim - 512 ? sv : -INFINITY;
;             S[rb][reg] = sv; mx = fmaxf(mx, sv); }
;     mx = tok ? mx : -INFINITY;
;     mx = pairmax32(mx);
;     const bool need = mx > RESC_THR || (inited == 0.f && mx > -INFINITY);
;     if (__builtin_amdgcn_ballot_w64(need) != 0ull) {
;         float delta = 0.f;
;         if (mx > -INFINITY) { delta = inited == 0.f ? mx : fmaxf(mx, 0.f); inited = 1.f; }
;         const float alpha = ex2(-delta);
;         l *= alpha;
; #pragma unroll
;         for (int reg = 0; reg < 16; ++reg) { O[0][reg] *= alpha; O[1][reg] *= alpha; negm[reg] -= delta; S[0][reg] -= delta; S[1][reg] -= delta; }
;     }
.Lnsa_nomid_b:
	s_waitcnt lgkmcnt(0)
	s_nop 10
	v_pk_add_f32 v[208:209], v[50:51], v[66:67]
	v_pk_add_f32 v[206:207], v[52:53], v[68:69]
	v_max3_f32 v50, v98, v208, v209
	v_max3_f32 v50, v50, v206, v207
	v_pk_add_f32 v[200:201], v[54:55], v[70:71]
	v_pk_add_f32 v[194:195], v[56:57], v[72:73]
	v_max3_f32 v50, v50, v200, v201
	v_max3_f32 v66, v50, v194, v195
	v_add_u32_e32 v50, 0x8f0c, v233
	ds_read2_b32 v[50:51], v50 offset1:1
	v_add_u32_e32 v52, 0x8f14, v233
	v_add_u32_e32 v54, 0x8f2c, v233
	v_add_u32_e32 v56, 0x8f34, v233
	ds_read2_b32 v[52:53], v52 offset1:1
	ds_read2_b32 v[54:55], v54 offset1:1
	ds_read2_b32 v[56:57], v56 offset1:1
	s_waitcnt lgkmcnt(0)
	v_pk_add_f32 v[214:215], v[58:59], v[50:51]
	v_pk_add_f32 v[212:213], v[60:61], v[52:53]
	v_max3_f32 v50, v66, v214, v215
	v_max3_f32 v50, v50, v212, v213
	v_pk_add_f32 v[210:211], v[62:63], v[54:55]
	v_pk_add_f32 v[216:217], v[64:65], v[56:57]
	v_max3_f32 v50, v50, v210, v211
	v_max3_f32 v50, v50, v216, v217
	v_cndmask_b32_e64 v50, v221, v50, s[2:3]
	v_mov_b32_e32 v51, v50
	s_nop 1
	v_permlane32_swap_b32_e32 v50, v51
	v_cmp_nlt_f32_e32 vcc, s67, v50
	s_and_saveexec_b64 s[0:1], vcc
	s_mov_b32 s6, 0xff800000
	v_cmp_eq_f32_e32 vcc, 0, v232
	v_cmp_lg_f32_e64 s[6:7], s6, v50
	s_and_b64 s[6:7], vcc, s[6:7]
	s_orn2_b64 s[6:7], s[6:7], exec
	s_or_b64 exec, exec, s[0:1]
	v_cndmask_b32_e64 v51, 0, 1, s[6:7]
	v_cmp_ne_u32_e32 vcc, 0, v51
	s_cbranch_vccz .LBB0_2055
	v_max_f32_e32 v51, v50, v50
	v_max_f32_e32 v51, 0, v51
	v_cmp_eq_f32_e32 vcc, 0, v232
	s_mov_b32 s0, 0xff800000
	s_nop 0
	v_cndmask_b32_e32 v51, v51, v50, vcc
	v_cmp_nlg_f32_e32 vcc, s0, v50
	s_nop 1
	v_cndmask_b32_e64 v239, v51, 0, vcc
	v_exp_f32_e64 v50, -v239
	v_cndmask_b32_e32 v235, 1.0, v232, vcc
	v_sub_f32_e32 v113, v97, v239
	v_sub_f32_e32 v112, v96, v239
	v_mul_f32_e32 v238, v231, v50
	v_pk_mul_f32 v[80:81], v[48:49], v[50:51] op_sel_hi:[1,0]
	v_pk_mul_f32 v[78:79], v[46:47], v[50:51] op_sel_hi:[1,0]
	v_pk_mul_f32 v[76:77], v[44:45], v[50:51] op_sel_hi:[1,0]
	v_pk_mul_f32 v[74:75], v[42:43], v[50:51] op_sel_hi:[1,0]
	v_pk_mul_f32 v[72:73], v[40:41], v[50:51] op_sel_hi:[1,0]
	v_pk_mul_f32 v[70:71], v[38:39], v[50:51] op_sel_hi:[1,0]
	v_pk_mul_f32 v[68:69], v[36:37], v[50:51] op_sel_hi:[1,0]
	v_pk_mul_f32 v[66:67], v[34:35], v[50:51] op_sel_hi:[1,0]
	v_pk_mul_f32 v[64:65], v[32:33], v[50:51] op_sel_hi:[1,0]
	v_pk_mul_f32 v[62:63], v[30:31], v[50:51] op_sel_hi:[1,0]
	v_pk_mul_f32 v[60:61], v[28:29], v[50:51] op_sel_hi:[1,0]
	v_pk_mul_f32 v[58:59], v[26:27], v[50:51] op_sel_hi:[1,0]
	v_pk_mul_f32 v[56:57], v[24:25], v[50:51] op_sel_hi:[1,0]
	v_pk_mul_f32 v[54:55], v[22:23], v[50:51] op_sel_hi:[1,0]
	v_pk_mul_f32 v[52:53], v[20:21], v[50:51] op_sel_hi:[1,0]
	v_pk_mul_f32 v[50:51], v[18:19], v[50:51] op_sel_hi:[1,0]
	v_sub_f32_e32 v111, v95, v239
	v_sub_f32_e32 v110, v94, v239
	v_sub_f32_e32 v109, v93, v239
	v_sub_f32_e32 v108, v92, v239
	v_sub_f32_e32 v107, v91, v239
	v_sub_f32_e32 v106, v90, v239
	v_sub_f32_e32 v105, v89, v239
	v_sub_f32_e32 v104, v88, v239
	v_sub_f32_e32 v103, v87, v239
	v_sub_f32_e32 v102, v86, v239
	v_sub_f32_e32 v101, v85, v239
	v_sub_f32_e32 v100, v84, v239
	v_sub_f32_e32 v99, v83, v239
	v_sub_f32_e32 v98, v82, v239
	v_sub_f32_e32 v202, v202, v239
	v_sub_f32_e32 v203, v203, v239
	v_sub_f32_e32 v198, v198, v239
	v_sub_f32_e32 v199, v199, v239
	v_sub_f32_e32 v138, v138, v239
	v_sub_f32_e32 v139, v139, v239
	v_sub_f32_e32 v16, v16, v239
	v_sub_f32_e32 v17, v17, v239
	v_sub_f32_e32 v204, v204, v239
	v_sub_f32_e32 v205, v205, v239
	v_sub_f32_e32 v196, v196, v239
	v_sub_f32_e32 v197, v197, v239
	v_sub_f32_e32 v140, v140, v239
	v_sub_f32_e32 v141, v141, v239
	v_sub_f32_e32 v192, v192, v239
	v_sub_f32_e32 v193, v193, v239
	v_sub_f32_e32 v208, v208, v239
	v_sub_f32_e32 v209, v209, v239
	v_sub_f32_e32 v206, v206, v239
	v_sub_f32_e32 v207, v207, v239
	v_sub_f32_e32 v200, v200, v239
	v_sub_f32_e32 v201, v201, v239
	v_sub_f32_e32 v194, v194, v239
	v_sub_f32_e32 v195, v195, v239
	v_sub_f32_e32 v214, v214, v239
	v_sub_f32_e32 v215, v215, v239
	v_sub_f32_e32 v212, v212, v239
	v_sub_f32_e32 v213, v213, v239
	v_sub_f32_e32 v210, v210, v239
	v_sub_f32_e32 v211, v211, v239
	v_sub_f32_e32 v216, v216, v239
	v_sub_f32_e32 v217, v217, v239
	s_branch .LBB0_2056

; #define LAS __attribute__((address_space(3)))
; #define MFMA32(a, b, c) __builtin_amdgcn_mfma_f32_32x32x16_bf16((a), (b), (c), 0, 0, 0)
; DI float ex2(float x) { return __builtin_amdgcn_exp2f(x); }
; template <bool NEAR, int MASK>
; DI void nsa_tile2(f32x16 (&O)[2], float& l, float& inited, f32x16& negm, const LAS unsigned char* Kb, const LAS unsigned char* Vb, const int (&ka)[4], const int (&va)[4], const bf16x8 (&qf)[4],
;                   const LAS float* lutp, float c31, int dlim, bool tok) {
;     f32x16 S[2];
; #pragma unroll
;     for (int rb = 0; rb < 2; ++rb) { const bf16x8 kf0 = *(const LAS bf16x8*)(Kb + ka[0] + rb * 4096); S[rb] = MFMA32(kf0, qf[0], negm);
; #pragma unroll
;         for (int ks = 1; ks < 4; ++ks) { const bf16x8 kf = *(const LAS bf16x8*)(Kb + ka[ks] + rb * 4096); S[rb] = MFMA32(kf, qf[ks], S[rb]); } }
;     float mx = -INFINITY;
; #pragma unroll
;     for (int rb = 0; rb < 2; ++rb)
; #pragma unroll
;         for (int reg = 0; reg < 16; ++reg) { const int c = 32 * rb + (reg & 3) + 8 * (reg >> 2); float sv = S[rb][reg];
;             if (NEAR) sv += lutp[c]; else sv += c31;
;             if (MASK == 1) sv = c <= dlim ? sv : -INFINITY;
;             if (MASK == 2) sv = c > dlim - 512 ? sv : -INFINITY;
;             S[rb][reg] = sv; mx = fmaxf(mx, sv); }
;     mx = tok ? mx : -INFINITY;
;     mx = pairmax32(mx);
;     const bool need = mx > RESC_THR || (inited == 0.f && mx > -INFINITY);
;     if (__builtin_amdgcn_ballot_w64(need) != 0ull) {
;         float delta = 0.f;
;         if (mx > -INFINITY) { delta = inited == 0.f ? mx : fmaxf(mx, 0.f); inited = 1.f; }
;         const float alpha = ex2(-delta);
;         l *= alpha;
; #pragma unroll
;         for (int reg = 0; reg < 16; ++reg) { O[0][reg] *= alpha; O[1][reg] *= alpha; negm[reg] -= delta; S[0][reg] -= delta; S[1][reg] -= delta; }
;     }
.LBB0_2057:
	s_and_b64 vcc, exec, s[0:1]
	s_cbranch_vccz .LBB0_2062
	s_waitcnt lgkmcnt(0)
	v_mfma_f32_32x32x16_bf16 v[66:81], v[134:137], v[114:117], v[82:97]
	s_mov_b32 s0, 0xff800000
	s_mov_b64 s[6:7], -1
	v_mfma_f32_32x32x16_bf16 v[66:81], v[130:133], v[118:121], v[66:81]
	v_mfma_f32_32x32x16_bf16 v[66:81], v[4:7], v[122:125], v[66:81]
	v_mfma_f32_32x32x16_bf16 v[50:65], v[12:15], v[114:117], v[82:97]
	v_mfma_f32_32x32x16_bf16 v[66:81], v[8:11], v[126:129], v[66:81]
	ds_read_b128 v[4:7], v237 offset:4096
	ds_read_b128 v[8:11], v234 offset:4096
	ds_read_b128 v[12:15], v236 offset:4096
	s_waitcnt lgkmcnt(0)
	v_mfma_f32_32x32x16_bf16 v[50:65], v[4:7], v[118:121], v[50:65]
	s_nop 6
	v_add_f32_e64 v196, v190, v66
	v_add_f32_e64 v197, v191, v67
	v_add_f32_e64 v194, v190, v68
	v_add_f32_e64 v195, v191, v69
	v_max3_f32 v16, v196, s0, v197
	v_max3_f32 v4, v16, v194, v195
	v_pk_add_f32 v[192:193], v[190:191], v[70:71]
	v_pk_add_f32 v[140:141], v[190:191], v[72:73]
	v_max3_f32 v4, v4, v192, v193
	v_mfma_f32_32x32x16_bf16 v[50:65], v[8:11], v[122:125], v[50:65]
	v_max3_f32 v4, v4, v140, v141
	v_add_f32_e64 v138, v190, v74
	v_add_f32_e64 v139, v191, v75
	v_add_f32_e64 v136, v190, v76
	v_add_f32_e64 v137, v191, v77
	v_max3_f32 v4, v4, v138, v139
	v_max3_f32 v4, v4, v136, v137
	v_pk_add_f32 v[134:135], v[190:191], v[78:79]
	v_pk_add_f32 v[132:133], v[190:191], v[80:81]
	v_mfma_f32_32x32x16_bf16 v[50:65], v[12:15], v[126:129], v[50:65]
	s_cmp_eq_u32 s98, 0
	s_cbranch_scc1 .Lnsa_nomid_c
	s_waitcnt vmcnt(0) lgkmcnt(0)
	s_barrier
	s_mov_b32 s99, 1
.Lnsa_nomid_c:
	v_max3_f32 v4, v4, v134, v135
	v_max3_f32 v4, v4, v132, v133
	s_nop 9
	v_pk_add_f32 v[130:131], v[190:191], v[50:51]
	v_pk_add_f32 v[16:17], v[190:191], v[52:53]
	v_max3_f32 v4, v4, v130, v131
	v_max3_f32 v4, v4, v16, v17
	v_pk_add_f32 v[6:7], v[190:191], v[54:55]
	v_pk_add_f32 v[14:15], v[190:191], v[58:59]
	v_max3_f32 v8, v4, v6, v7
	v_pk_add_f32 v[4:5], v[190:191], v[56:57]
	s_nop 0
	v_max3_f32 v8, v8, v4, v5
	v_max3_f32 v10, v8, v14, v15
	v_pk_add_f32 v[8:9], v[190:191], v[60:61]
	s_nop 0
	v_max3_f32 v12, v10, v8, v9
	v_pk_add_f32 v[10:11], v[190:191], v[62:63]
	s_nop 0
	v_max3_f32 v50, v12, v10, v11
	v_pk_add_f32 v[12:13], v[190:191], v[64:65]
	s_nop 0
	v_max3_f32 v50, v50, v12, v13
	v_cndmask_b32_e64 v50, v221, v50, s[4:5]
	v_mov_b32_e32 v51, v50
	s_nop 1
	v_permlane32_swap_b32_e32 v50, v51
	v_cmp_nlt_f32_e32 vcc, s67, v50
	s_and_saveexec_b64 s[0:1], vcc
	s_mov_b32 s6, 0xff800000
	v_cmp_eq_f32_e32 vcc, 0, v232
	v_cmp_lg_f32_e64 s[6:7], s6, v50
	s_and_b64 s[6:7], vcc, s[6:7]
	s_orn2_b64 s[6:7], s[6:7], exec
	s_or_b64 exec, exec, s[0:1]
	v_cndmask_b32_e64 v51, 0, 1, s[6:7]
	v_cmp_ne_u32_e32 vcc, 0, v51
	s_cbranch_vccz .LBB0_2074
	v_max_f32_e32 v51, v50, v50
	v_max_f32_e32 v51, 0, v51
	v_cmp_eq_f32_e32 vcc, 0, v232
	s_mov_b32 s0, 0xff800000
	s_nop 0
	v_cndmask_b32_e32 v51, v51, v50, vcc
	v_cmp_nlg_f32_e32 vcc, s0, v50
	s_nop 1
	v_cndmask_b32_e64 v199, v51, 0, vcc
	v_exp_f32_e64 v50, -v199
	v_cndmask_b32_e32 v235, 1.0, v232, vcc
	v_sub_f32_e32 v113, v97, v199
	v_sub_f32_e32 v112, v96, v199
	v_mul_f32_e32 v198, v231, v50
	v_pk_mul_f32 v[80:81], v[48:49], v[50:51] op_sel_hi:[1,0]
	v_pk_mul_f32 v[78:79], v[46:47], v[50:51] op_sel_hi:[1,0]
	v_pk_mul_f32 v[76:77], v[44:45], v[50:51] op_sel_hi:[1,0]
	v_pk_mul_f32 v[74:75], v[42:43], v[50:51] op_sel_hi:[1,0]
	v_pk_mul_f32 v[72:73], v[40:41], v[50:51] op_sel_hi:[1,0]
	v_pk_mul_f32 v[70:71], v[38:39], v[50:51] op_sel_hi:[1,0]
	v_pk_mul_f32 v[68:69], v[36:37], v[50:51] op_sel_hi:[1,0]
	v_pk_mul_f32 v[66:67], v[34:35], v[50:51] op_sel_hi:[1,0]
	v_pk_mul_f32 v[64:65], v[32:33], v[50:51] op_sel_hi:[1,0]
	v_pk_mul_f32 v[62:63], v[30:31], v[50:51] op_sel_hi:[1,0]
	v_pk_mul_f32 v[60:61], v[28:29], v[50:51] op_sel_hi:[1,0]
	v_pk_mul_f32 v[58:59], v[26:27], v[50:51] op_sel_hi:[1,0]
	v_pk_mul_f32 v[56:57], v[24:25], v[50:51] op_sel_hi:[1,0]
	v_pk_mul_f32 v[54:55], v[22:23], v[50:51] op_sel_hi:[1,0]
	v_pk_mul_f32 v[52:53], v[20:21], v[50:51] op_sel_hi:[1,0]
	v_pk_mul_f32 v[50:51], v[18:19], v[50:51] op_sel_hi:[1,0]
	v_sub_f32_e32 v111, v95, v199
	v_sub_f32_e32 v110, v94, v199
	v_sub_f32_e32 v109, v93, v199
	v_sub_f32_e32 v108, v92, v199
	v_sub_f32_e32 v107, v91, v199
	v_sub_f32_e32 v106, v90, v199
	v_sub_f32_e32 v105, v89, v199
	v_sub_f32_e32 v104, v88, v199
	v_sub_f32_e32 v103, v87, v199
	v_sub_f32_e32 v102, v86, v199
	v_sub_f32_e32 v101, v85, v199
	v_sub_f32_e32 v100, v84, v199
	v_sub_f32_e32 v99, v83, v199
	v_sub_f32_e32 v98, v82, v199
	v_sub_f32_e32 v196, v196, v199
	v_sub_f32_e32 v197, v197, v199
	v_sub_f32_e32 v194, v194, v199
	v_sub_f32_e32 v195, v195, v199
	v_sub_f32_e32 v192, v192, v199
	v_sub_f32_e32 v193, v193, v199
	v_sub_f32_e32 v140, v140, v199
	v_sub_f32_e32 v141, v141, v199
	v_sub_f32_e32 v138, v138, v199
	v_sub_f32_e32 v139, v139, v199
	v_sub_f32_e32 v136, v136, v199
	v_sub_f32_e32 v137, v137, v199
	v_sub_f32_e32 v134, v134, v199
	v_sub_f32_e32 v135, v135, v199
	v_sub_f32_e32 v132, v132, v199
	v_sub_f32_e32 v133, v133, v199
	v_sub_f32_e32 v130, v130, v199
	v_sub_f32_e32 v131, v131, v199
	v_sub_f32_e32 v16, v16, v199
	v_sub_f32_e32 v17, v17, v199
	v_sub_f32_e32 v6, v6, v199
	v_sub_f32_e32 v7, v7, v199
	v_sub_f32_e32 v4, v4, v199
	v_sub_f32_e32 v5, v5, v199
	v_sub_f32_e32 v14, v14, v199
	v_sub_f32_e32 v15, v15, v199
	v_sub_f32_e32 v8, v8, v199
	v_sub_f32_e32 v9, v9, v199
	v_sub_f32_e32 v10, v10, v199
	v_sub_f32_e32 v11, v11, v199
	v_sub_f32_e32 v12, v12, v199
	v_sub_f32_e32 v13, v13, v199
	s_branch .LBB0_2075

; #define LAS __attribute__((address_space(3)))
; #define MFMA32(a, b, c) __builtin_amdgcn_mfma_f32_32x32x16_bf16((a), (b), (c), 0, 0, 0)
; template <bool NEAR, int MASK>
; DI void nsa_tile2(f32x16 (&O)[2], float& l, float& inited, f32x16& negm, const LAS unsigned char* Kb, const LAS unsigned char* Vb, const int (&ka)[4], const int (&va)[4], const bf16x8 (&qf)[4],
;                   const LAS float* lutp, float c31, int dlim, bool tok) {
;     f32x16 S[2];
; #pragma unroll
;     for (int rb = 0; rb < 2; ++rb) { const bf16x8 kf0 = *(const LAS bf16x8*)(Kb + ka[0] + rb * 4096); S[rb] = MFMA32(kf0, qf[0], negm);
; #pragma unroll
;         for (int ks = 1; ks < 4; ++ks) { const bf16x8 kf = *(const LAS bf16x8*)(Kb + ka[ks] + rb * 4096); S[rb] = MFMA32(kf, qf[ks], S[rb]); } }
;     float mx = -INFINITY;
; #pragma unroll
;     for (int rb = 0; rb < 2; ++rb)
; #pragma unroll
;         for (int reg = 0; reg < 16; ++reg) { const int c = 32 * rb + (reg & 3) + 8 * (reg >> 2); float sv = S[rb][reg];
;             if (NEAR) sv += lutp[c]; else sv += c31;
;             if (MASK == 1) sv = c <= dlim ? sv : -INFINITY;
;             if (MASK == 2) sv = c > dlim - 512 ? sv : -INFINITY;
;             S[rb][reg] = sv; mx = fmaxf(mx, sv); }
; DI void nsa_unit(const Args& a, LAS unsigned char* lds, int b, int g, int jb) {
;     ...
;                 if (kt == jb) nsa_tile2<true, 1>(O, l, inited, negm, Kb, Vb, ka, va, qf, lutp, c31, dlim, tok);
.LBB0_2064:
	s_waitcnt lgkmcnt(0)
	v_add_u32_e32 v8, s20, v223
	ds_read_b128 v[4:7], v8
	ds_read_b128 v[12:15], v8 offset:4096
	v_add_u32_e32 v9, s20, v224
	v_add_u32_e32 v16, 0x8e4c, v233
	v_add_u32_e32 v17, 0x8e6c, v233
	v_add_u32_e32 v106, 0x8e74, v233
	v_cmp_lt_i32_e32 vcc, 0, v3
	s_mov_b32 s0, 0xff800000
	s_mov_b64 s[4:5], -1
	s_waitcnt lgkmcnt(0)
	v_mfma_f32_32x32x16_bf16 v[66:81], v[4:7], v[114:117], v[82:97]
	ds_read_b128 v[4:7], v9
	ds_read_b128 v[98:101], v9 offset:4096
	s_waitcnt lgkmcnt(0)
	v_mfma_f32_32x32x16_bf16 v[66:81], v[4:7], v[118:121], v[66:81]
	ds_read_b128 v[4:7], v234
	ds_read_b128 v[8:11], v234 offset:4096
	s_waitcnt lgkmcnt(0)
	v_mfma_f32_32x32x16_bf16 v[66:81], v[4:7], v[122:125], v[66:81]
	v_add_u32_e32 v4, s20, v226
	ds_read_b128 v[102:105], v4
	ds_read_b128 v[4:7], v4 offset:4096
	s_waitcnt lgkmcnt(0)
	v_mfma_f32_32x32x16_bf16 v[66:81], v[102:105], v[126:129], v[66:81]
	v_mfma_f32_32x32x16_bf16 v[50:65], v[12:15], v[114:117], v[82:97]
	v_add_u32_e32 v14, 0x8e54, v233
	ds_read2_b32 v[12:13], v16 offset1:1
	ds_read2_b32 v[14:15], v14 offset1:1
	ds_read2_b32 v[16:17], v17 offset1:1
	ds_read2_b32 v[106:107], v106 offset1:1
	s_waitcnt lgkmcnt(0)
	s_nop 4
	v_pk_add_f32 v[12:13], v[66:67], v[12:13]
	s_nop 0
	v_cndmask_b32_e32 v66, v221, v13, vcc
	v_cmp_lt_i32_e32 vcc, -1, v3
	v_pk_add_f32 v[14:15], v[68:69], v[14:15]
	v_mfma_f32_32x32x16_bf16 v[50:65], v[98:101], v[118:121], v[50:65]
	v_cndmask_b32_e32 v68, v221, v12, vcc
	v_cmp_lt_i32_e32 vcc, 2, v3
	v_add_f32_e64 v70, v70, v16
	v_add_f32_e64 v71, v71, v17
	v_add_f32_e64 v72, v72, v106
	v_add_f32_e64 v73, v73, v107
	v_cndmask_b32_e32 v16, v221, v15, vcc
	v_cmp_lt_i32_e32 vcc, 1, v3
	v_max3_f32 v12, v68, s0, v66
	v_mfma_f32_32x32x16_bf16 v[50:65], v[8:11], v[122:125], v[50:65]
	v_cndmask_b32_e32 v67, v221, v14, vcc
	v_cmp_lt_i32_e32 vcc, 8, v3
	v_max3_f32 v12, v12, v67, v16
	s_nop 0
	v_cndmask_b32_e32 v14, v221, v71, vcc
	v_cmp_lt_i32_e32 vcc, 7, v3
	v_add_u32_e32 v71, 0x8eac, v233
	v_mfma_f32_32x32x16_bf16 v[50:65], v[4:7], v[126:129], v[50:65]
	s_cmp_eq_u32 s98, 0
	s_cbranch_scc1 .Lnsa_nomid_d
	s_waitcnt vmcnt(0) lgkmcnt(0)
	s_barrier
	s_mov_b32 s99, 1
; DI float ex2(float x) { return __builtin_amdgcn_exp2f(x); }
; template <bool NEAR, int MASK>
; DI void nsa_tile2(f32x16 (&O)[2], float& l, float& inited, f32x16& negm, const LAS unsigned char* Kb, const LAS unsigned char* Vb, const int (&ka)[4], const int (&va)[4], const bf16x8 (&qf)[4],
;                   const LAS float* lutp, float c31, int dlim, bool tok) {
;     ...
;     float mx = -INFINITY;
; #pragma unroll
;     for (int rb = 0; rb < 2; ++rb)
; #pragma unroll
;         for (int reg = 0; reg < 16; ++reg) { const int c = 32 * rb + (reg & 3) + 8 * (reg >> 2); float sv = S[rb][reg];
;             if (NEAR) sv += lutp[c]; else sv += c31;
;             if (MASK == 1) sv = c <= dlim ? sv : -INFINITY;
;             if (MASK == 2) sv = c > dlim - 512 ? sv : -INFINITY;
;             S[rb][reg] = sv; mx = fmaxf(mx, sv); }
;     mx = tok ? mx : -INFINITY;
;     mx = pairmax32(mx);
;     const bool need = mx > RESC_THR || (inited == 0.f && mx > -INFINITY);
;     if (__builtin_amdgcn_ballot_w64(need) != 0ull) {
;         float delta = 0.f;
;         if (mx > -INFINITY) { delta = inited == 0.f ? mx : fmaxf(mx, 0.f); inited = 1.f; }
;         const float alpha = ex2(-delta);
;         l *= alpha;
; #pragma unroll
;         for (int reg = 0; reg < 16; ++reg) { O[0][reg] *= alpha; O[1][reg] *= alpha; negm[reg] -= delta; S[0][reg] -= delta; S[1][reg] -= delta; }
;     }
.Lnsa_nomid_d:
	v_cndmask_b32_e32 v15, v221, v70, vcc
	v_cmp_lt_i32_e32 vcc, 10, v3
	v_max3_f32 v12, v12, v15, v14
	v_add_u32_e32 v70, 0x8e94, v233
	v_cndmask_b32_e32 v17, v221, v73, vcc
	v_cmp_lt_i32_e32 vcc, 9, v3
	s_nop 1
	v_cndmask_b32_e32 v69, v221, v72, vcc
	v_max3_f32 v98, v12, v69, v17
	v_add_u32_e32 v12, 0x8e8c, v233
	ds_read2_b32 v[12:13], v12 offset1:1
	v_add_u32_e32 v72, 0x8eb4, v233
	ds_read2_b32 v[8:9], v70 offset1:1
	ds_read2_b32 v[10:11], v71 offset1:1
	ds_read2_b32 v[72:73], v72 offset1:1
	v_cmp_lt_i32_e32 vcc, 16, v3
	s_waitcnt lgkmcnt(0)
	v_pk_add_f32 v[12:13], v[74:75], v[12:13]
	s_nop 0
	v_cndmask_b32_e32 v70, v221, v13, vcc
	v_cmp_lt_i32_e32 vcc, 15, v3
	v_pk_add_f32 v[4:5], v[76:77], v[8:9]
	v_pk_add_f32 v[8:9], v[78:79], v[10:11]
	v_cndmask_b32_e32 v71, v221, v12, vcc
	v_cmp_lt_i32_e32 vcc, 18, v3
	v_max3_f32 v6, v98, v71, v70
	v_add_u32_e32 v75, 0x8ef4, v233
	v_cndmask_b32_e32 v5, v221, v5, vcc
	v_cmp_lt_i32_e32 vcc, 17, v3
	s_nop 1
	v_cndmask_b32_e32 v7, v221, v4, vcc
	v_cmp_lt_i32_e32 vcc, 24, v3
	v_max3_f32 v12, v6, v7, v5
	s_nop 0
	v_cndmask_b32_e32 v4, v221, v9, vcc
	v_cmp_lt_i32_e32 vcc, 23, v3
	s_nop 1
	v_cndmask_b32_e32 v6, v221, v8, vcc
	v_pk_add_f32 v[8:9], v[80:81], v[72:73]
	v_cmp_lt_i32_e32 vcc, 26, v3
	v_max3_f32 v10, v12, v6, v4
	v_add_u32_e32 v12, 0x8eec, v233
	v_cndmask_b32_e32 v72, v221, v9, vcc
	v_cmp_lt_i32_e32 vcc, 25, v3
	s_nop 1
	v_cndmask_b32_e32 v73, v221, v8, vcc
	v_add_u32_e32 v8, 0x8ecc, v233
	ds_read2_b32 v[8:9], v8 offset1:1
	v_max3_f32 v74, v10, v73, v72
	v_add_u32_e32 v10, 0x8ed4, v233
	ds_read2_b32 v[10:11], v10 offset1:1
	ds_read2_b32 v[12:13], v12 offset1:1
	ds_read2_b32 v[78:79], v75 offset1:1
	v_cmp_lt_i32_e32 vcc, 32, v3
	s_waitcnt lgkmcnt(0)
	v_pk_add_f32 v[8:9], v[50:51], v[8:9]
	s_nop 0
	v_cndmask_b32_e32 v75, v221, v9, vcc
	v_cmp_lt_i32_e32 vcc, 31, v3
	s_nop 1
	v_cndmask_b32_e32 v76, v221, v8, vcc
	v_pk_add_f32 v[8:9], v[52:53], v[10:11]
	v_cmp_lt_i32_e32 vcc, 34, v3
	v_max3_f32 v50, v74, v76, v75
	v_add_u32_e32 v11, 0x8f14, v233
	v_cndmask_b32_e32 v52, v221, v9, vcc
	v_cmp_lt_i32_e32 vcc, 33, v3
	s_nop 1
	v_cndmask_b32_e32 v74, v221, v8, vcc
	v_pk_add_f32 v[8:9], v[54:55], v[12:13]
	v_cmp_lt_i32_e32 vcc, 40, v3
	v_add_u32_e32 v12, 0x8f2c, v233
	v_add_u32_e32 v13, 0x8f34, v233
	v_cndmask_b32_e32 v51, v221, v9, vcc
	v_cmp_lt_i32_e32 vcc, 39, v3
	v_max3_f32 v10, v50, v74, v52
	s_nop 0
	v_cndmask_b32_e32 v53, v221, v8, vcc
	v_pk_add_f32 v[8:9], v[56:57], v[78:79]
	v_cmp_lt_i32_e32 vcc, 42, v3
	v_max3_f32 v10, v10, v53, v51
	s_nop 0
	v_cndmask_b32_e32 v54, v221, v9, vcc
	v_cmp_lt_i32_e32 vcc, 41, v3
	s_nop 1
	v_cndmask_b32_e32 v55, v221, v8, vcc
	v_add_u32_e32 v8, 0x8f0c, v233
	ds_read2_b32 v[8:9], v8 offset1:1
	ds_read2_b32 v[56:57], v11 offset1:1
	ds_read2_b32 v[78:79], v12 offset1:1
	ds_read2_b32 v[80:81], v13 offset1:1
	v_cmp_lt_i32_e32 vcc, 48, v3
	v_max3_f32 v10, v10, v55, v54
	s_waitcnt lgkmcnt(0)
	v_pk_add_f32 v[56:57], v[60:61], v[56:57]
	v_pk_add_f32 v[8:9], v[58:59], v[8:9]
	s_nop 0
	v_cndmask_b32_e32 v11, v221, v9, vcc
	v_cmp_lt_i32_e32 vcc, 47, v3
	s_nop 1
	v_cndmask_b32_e32 v12, v221, v8, vcc
	v_cmp_lt_i32_e32 vcc, 50, v3
	v_max3_f32 v9, v10, v12, v11
	s_nop 0
	v_cndmask_b32_e32 v8, v221, v57, vcc
	v_cmp_lt_i32_e32 vcc, 49, v3
	s_nop 1
	v_cndmask_b32_e32 v13, v221, v56, vcc
	v_pk_add_f32 v[56:57], v[62:63], v[78:79]
	v_cmp_lt_i32_e32 vcc, 56, v3
	v_max3_f32 v50, v9, v13, v8
	s_nop 0
	v_cndmask_b32_e32 v9, v221, v57, vcc
	v_cmp_lt_i32_e32 vcc, 55, v3
	s_nop 1
	v_cndmask_b32_e32 v10, v221, v56, vcc
	v_pk_add_f32 v[56:57], v[64:65], v[80:81]
	v_cmp_lt_i32_e32 vcc, 58, v3
	v_max3_f32 v58, v50, v10, v9
	s_nop 0
	v_cndmask_b32_e32 v50, v221, v57, vcc
	v_cmp_lt_i32_e32 vcc, 57, v3
	s_nop 1
	v_cndmask_b32_e32 v3, v221, v56, vcc
	v_max3_f32 v56, v58, v3, v50
	v_cndmask_b32_e64 v56, v221, v56, s[2:3]
	v_mov_b32_e32 v57, v56
	s_nop 1
	v_permlane32_swap_b32_e32 v56, v57
	v_cmp_nlt_f32_e32 vcc, s67, v56
	s_and_saveexec_b64 s[0:1], vcc
	s_mov_b32 s4, 0xff800000
	v_cmp_eq_f32_e32 vcc, 0, v232
	v_cmp_lg_f32_e64 s[4:5], s4, v56
	s_and_b64 s[4:5], vcc, s[4:5]
	s_orn2_b64 s[4:5], s[4:5], exec
	s_or_b64 exec, exec, s[0:1]
	v_cndmask_b32_e64 v57, 0, 1, s[4:5]
	v_cmp_ne_u32_e32 vcc, 0, v57
	s_cbranch_vccz .LBB0_2068
	v_max_f32_e32 v57, v56, v56
	v_max_f32_e32 v57, 0, v57
	v_cmp_eq_f32_e32 vcc, 0, v232
	s_mov_b32 s0, 0xff800000
	s_nop 0
	v_cndmask_b32_e32 v57, v57, v56, vcc
	v_cmp_nlg_f32_e32 vcc, s0, v56
	s_nop 1
	v_cndmask_b32_e64 v57, v57, 0, vcc
	v_exp_f32_e64 v56, -v57
	v_cndmask_b32_e32 v232, 1.0, v232, vcc
	v_sub_f32_e32 v97, v97, v57
	v_sub_f32_e32 v96, v96, v57
	v_mul_f32_e32 v231, v231, v56
	v_pk_mul_f32 v[48:49], v[48:49], v[56:57] op_sel_hi:[1,0]
	v_pk_mul_f32 v[46:47], v[46:47], v[56:57] op_sel_hi:[1,0]
	v_pk_mul_f32 v[44:45], v[44:45], v[56:57] op_sel_hi:[1,0]
	v_pk_mul_f32 v[42:43], v[42:43], v[56:57] op_sel_hi:[1,0]
	v_pk_mul_f32 v[40:41], v[40:41], v[56:57] op_sel_hi:[1,0]
	v_pk_mul_f32 v[38:39], v[38:39], v[56:57] op_sel_hi:[1,0]
	v_pk_mul_f32 v[36:37], v[36:37], v[56:57] op_sel_hi:[1,0]
	v_pk_mul_f32 v[34:35], v[34:35], v[56:57] op_sel_hi:[1,0]
	v_pk_mul_f32 v[32:33], v[32:33], v[56:57] op_sel_hi:[1,0]
	v_pk_mul_f32 v[30:31], v[30:31], v[56:57] op_sel_hi:[1,0]
	v_pk_mul_f32 v[28:29], v[28:29], v[56:57] op_sel_hi:[1,0]
	v_pk_mul_f32 v[26:27], v[26:27], v[56:57] op_sel_hi:[1,0]
	v_pk_mul_f32 v[24:25], v[24:25], v[56:57] op_sel_hi:[1,0]
	v_pk_mul_f32 v[22:23], v[22:23], v[56:57] op_sel_hi:[1,0]
	v_pk_mul_f32 v[20:21], v[20:21], v[56:57] op_sel_hi:[1,0]
	v_pk_mul_f32 v[18:19], v[18:19], v[56:57] op_sel_hi:[1,0]
	v_sub_f32_e32 v95, v95, v57
	v_sub_f32_e32 v94, v94, v57
	v_sub_f32_e32 v93, v93, v57
	v_sub_f32_e32 v92, v92, v57
	v_sub_f32_e32 v91, v91, v57
	v_sub_f32_e32 v90, v90, v57
	v_sub_f32_e32 v89, v89, v57
	v_sub_f32_e32 v88, v88, v57
	v_sub_f32_e32 v87, v87, v57
	v_sub_f32_e32 v86, v86, v57
	v_sub_f32_e32 v85, v85, v57
	v_sub_f32_e32 v84, v84, v57
	v_sub_f32_e32 v83, v83, v57
	v_sub_f32_e32 v82, v82, v57
	v_sub_f32_e32 v68, v68, v57
	v_sub_f32_e32 v66, v66, v57
	v_sub_f32_e32 v67, v67, v57
	v_sub_f32_e32 v16, v16, v57
	v_sub_f32_e32 v15, v15, v57
	v_sub_f32_e32 v14, v14, v57
	v_sub_f32_e32 v69, v69, v57
	v_sub_f32_e32 v17, v17, v57
	v_sub_f32_e32 v71, v71, v57
	v_sub_f32_e32 v70, v70, v57
	v_sub_f32_e32 v7, v7, v57
	v_sub_f32_e32 v5, v5, v57
	v_sub_f32_e32 v6, v6, v57
	v_sub_f32_e32 v4, v4, v57
	v_sub_f32_e32 v73, v73, v57
	v_sub_f32_e32 v72, v72, v57
	v_sub_f32_e32 v76, v76, v57
	v_sub_f32_e32 v75, v75, v57
	v_sub_f32_e32 v74, v74, v57
	v_sub_f32_e32 v52, v52, v57
	v_sub_f32_e32 v53, v53, v57
	v_sub_f32_e32 v51, v51, v57
	v_sub_f32_e32 v55, v55, v57
	v_sub_f32_e32 v54, v54, v57
	v_sub_f32_e32 v12, v12, v57
	v_sub_f32_e32 v11, v11, v57
	v_sub_f32_e32 v13, v13, v57
	v_sub_f32_e32 v8, v8, v57
	v_sub_f32_e32 v10, v10, v57
	v_sub_f32_e32 v9, v9, v57
	v_sub_f32_e32 v3, v3, v57
	v_sub_f32_e32 v50, v50, v57

; __global__ void __launch_bounds__(NWAVES * 64, 2) fwd(Args a) {
;     extern __shared__ __attribute__((aligned(16))) unsigned char lds_raw[];
	.amdhsa_kernel _Z3fwd4Args
		.amdhsa_group_segment_fixed_size 0
		.amdhsa_private_segment_fixed_size 0
		.amdhsa_kernarg_size 512
		.amdhsa_user_sgpr_count 2
		.amdhsa_user_sgpr_dispatch_ptr 0
		.amdhsa_user_sgpr_queue_ptr 0
		.amdhsa_user_sgpr_kernarg_segment_ptr 1
		.amdhsa_user_sgpr_dispatch_id 0
		.amdhsa_user_sgpr_kernarg_preload_length 0
		.amdhsa_user_sgpr_kernarg_preload_offset 0
		.amdhsa_user_sgpr_private_segment_size 0
		.amdhsa_uses_dynamic_stack 0
		.amdhsa_enable_private_segment 0
		.amdhsa_system_sgpr_workgroup_id_x 1
		.amdhsa_system_sgpr_workgroup_id_y 0
		.amdhsa_system_sgpr_workgroup_id_z 0
		.amdhsa_system_sgpr_workgroup_info 0
		.amdhsa_system_vgpr_workitem_id 0
		.amdhsa_next_free_vgpr 255
		.amdhsa_next_free_sgpr 102
		.amdhsa_accum_offset 256
		.amdhsa_reserve_vcc 1
		.amdhsa_float_round_mode_32 0
		.amdhsa_float_round_mode_16_64 0
		.amdhsa_float_denorm_mode_32 3
		.amdhsa_float_denorm_mode_16_64 3
		.amdhsa_dx10_clamp 1
		.amdhsa_ieee_mode 1
		.amdhsa_fp16_overflow 0
		.amdhsa_tg_split 0
		.amdhsa_exception_fp_ieee_invalid_op 0
		.amdhsa_exception_fp_denorm_src 0
		.amdhsa_exception_fp_ieee_div_zero 0
		.amdhsa_exception_fp_ieee_overflow 0
		.amdhsa_exception_fp_ieee_underflow 0
		.amdhsa_exception_fp_ieee_inexact 0
		.amdhsa_exception_int_div_zero 0
	.end_amdhsa_kernel

; __global__ void __launch_bounds__(NWAVES * 64, 2) fwd(Args a) {
;     extern __shared__ __attribute__((aligned(16))) unsigned char lds_raw[];
amdhsa.kernels:
  - .agpr_count:     0
    .args:
      - .offset:         0
        .size:           256
        .value_kind:     by_value
      - .offset:         256
        .size:           4
        .value_kind:     hidden_block_count_x
      - .offset:         260
        .size:           4
        .value_kind:     hidden_block_count_y
      - .offset:         264
        .size:           4
        .value_kind:     hidden_block_count_z
      - .offset:         268
        .size:           2
        .value_kind:     hidden_group_size_x
      - .offset:         270
        .size:           2
        .value_kind:     hidden_group_size_y
      - .offset:         272
        .size:           2
        .value_kind:     hidden_group_size_z
      - .offset:         274
        .size:           2
        .value_kind:     hidden_remainder_x
      - .offset:         276
        .size:           2
        .value_kind:     hidden_remainder_y
      - .offset:         278
        .size:           2
        .value_kind:     hidden_remainder_z
      - .offset:         296
        .size:           8
        .value_kind:     hidden_global_offset_x
      - .offset:         304
        .size:           8
        .value_kind:     hidden_global_offset_y
      - .offset:         312
        .size:           8
        .value_kind:     hidden_global_offset_z
      - .offset:         320
        .size:           2
        .value_kind:     hidden_grid_dims
      - .offset:         376
        .size:           4
        .value_kind:     hidden_dynamic_lds_size
    .group_segment_fixed_size: 0
    .kernarg_segment_align: 8
    .kernarg_segment_size: 512
    .language:       OpenCL C
    .language_version:
      - 2
      - 0
    .max_flat_workgroup_size: 512
    .name:           _Z3fwd4Args
    .private_segment_fixed_size: 0
    .sgpr_count:     108
    .sgpr_spill_count: 232
    .symbol:         _Z3fwd4Args.kd
    .uniform_work_group_size: 1
    .uses_dynamic_stack: false
    .vgpr_count:     255
    .vgpr_spill_count: 0
    .wavefront_size: 64
